# P5 tail rebalanced: GEMM CUs convert 3072 w_down items (2 per wave), tail CUs 7936
# baseline (speedup 1.0000x reference)
; #define LAS __attribute__((address_space(3)))
; __device__ __forceinline__ void cvt_range(const Args& a, int lo, int hi, int worker, int nworkers, LAS unsigned* T, int lane) {
;     int it = lo + worker;
;     f32x4 va[8], vb[8], wa[8], wb[8]; float sa[8], sb[8], ta[8], tb[8];
;     CvtItem c0{}, c1{};
;     if (it < hi) { cvt_decode(it, a, c0); cvt_load(c0, lane, va, vb, sa, sb); }
;     if (it + nworkers < hi) { cvt_decode(it + nworkers, a, c1); cvt_load(c1, lane, wa, wb, ta, tb); }
;     const int kq = lane >> 4, nq = lane & 15;
;     LAS unsigned* tw = T + (4 * nq) * 33 + kq;
;     const LAS unsigned* tr = T + (lane >> 3) * 33 + 4 * (lane & 7);
;     while (it < hi) {
; __global__ void __launch_bounds__(NWAVES * 64, 2) fwd_kernel(Args args) {
;     ...
;             const int nunits = (SEQ / 256) * (2 * DFF / 256), nfull = nunits % G;
;             if (!split_roles) {}
;             else if (nfull != 0 && bid >= nfull) cvt_range(args, CI_TOTAL - CI_D, CI_TOTAL, (bid - nfull) * NWAVES + wave, (G - nfull) * NWAVES, (LAS unsigned*)(lds + wave * 16384), lane);
;             else if (nfull == 0) cvt_range(args, CI_TOTAL - CI_D, CI_TOTAL, gw, NGW, (LAS unsigned*)(lds + wave * 16384), lane);
.LBB0_637:
	s_abs_i32 s2, s62
	v_cvt_f32_u32_e32 v0, s2
	s_sub_i32 s3, 0, s2
	s_mov_b32 s8, 0
	v_rcp_iflag_f32_e32 v0, v0
	s_nop 0
	v_mul_f32_e32 v0, 0x4f7ffffe, v0
	v_cvt_u32_f32_e32 v0, v0
	s_nop 0
	v_readfirstlane_b32 s4, v0
	s_mul_i32 s3, s3, s4
	s_mul_hi_u32 s3, s4, s3
	s_add_i32 s4, s4, s3
	s_mul_hi_u32 s3, s4, 0xac0
	s_mul_i32 s3, s3, s2
	s_sub_i32 s3, 0xac0, s3
	s_sub_i32 s4, s3, s2
	s_cmp_ge_u32 s3, s2
	s_cselect_b32 s3, s4, s3
	s_sub_i32 s4, s3, s2
	s_cmp_ge_u32 s3, s2
	s_cselect_b32 s2, s4, s3
	s_cmp_lt_i32 s55, s2
	v_readlane_b32 s4, v243, 27
	s_cselect_b64 s[2:3], -1, 0
	v_readlane_b32 s5, v243, 28
	s_or_b64 s[2:3], s[4:5], s[2:3]
	s_and_b64 vcc, exec, s[2:3]
	s_cbranch_vccnz .Lp5_nontail
	v_writelane_b32 v244, s0, 0
	v_writelane_b32 v244, s1, 1
	v_writelane_b32 v244, s46, 2
	v_writelane_b32 v244, s62, 3
	v_writelane_b32 v244, s64, 4
	v_writelane_b32 v244, s65, 5
	v_writelane_b32 v244, s66, 6
	v_writelane_b32 v244, s67, 7
	v_writelane_b32 v244, s68, 8
	v_writelane_b32 v244, s69, 9
	v_writelane_b32 v244, s70, 10
	v_writelane_b32 v244, s71, 11
	v_writelane_b32 v244, s88, 12
	v_writelane_b32 v244, s90, 13
	s_add_i32 s88, s94, 0x7500
	s_movk_i32 s62, 64
	s_mov_b32 s24, 0x9a00
	s_branch .Lp5_call
.Lp5_nontail:
	s_and_b64 vcc, exec, s[4:5]
	s_cbranch_vccnz .LBB0_731
	v_writelane_b32 v244, s0, 0
	v_writelane_b32 v244, s1, 1
	v_writelane_b32 v244, s46, 2
	v_writelane_b32 v244, s62, 3
	v_writelane_b32 v244, s64, 4
	v_writelane_b32 v244, s65, 5
	v_writelane_b32 v244, s66, 6
	v_writelane_b32 v244, s67, 7
	v_writelane_b32 v244, s68, 8
	v_writelane_b32 v244, s69, 9
	v_writelane_b32 v244, s70, 10
	v_writelane_b32 v244, s71, 11
	v_writelane_b32 v244, s88, 12
	v_writelane_b32 v244, s90, 13
	s_add_i32 s88, s94, 0x9a00
	s_movk_i32 s62, 192
	s_mov_b32 s24, 0xa600
